# speedup vs baseline: 1.0205x; 1.0205x over previous
; __device__ void phase1(const Params& p) {
;     ...
;     if (fo < 2048) { dst = (u16*)(ws + OFF_XA); ld = 2048; cofs = 0; act = 0; }
;     else if (fo < 4096) { dst = (u16*)(ws + OFF_ZA); ld = 2048; cofs = 2048; act = 1; }
;     else if (fo < 5120) { dst = (u16*)(ws + OFF_XB); ld = 1024; cofs = 4096; act = 0; }
;     else if (fo < 6144) { dst = (u16*)(ws + OFF_ZB); ld = 1024; cofs = 5120; act = 1; }
;     else if (fo < 8192) { dst = (u16*)(ws + OFF_SGA); ld = 2048; cofs = 6144; act = 2; }
;     else { dst = (u16*)(ws + OFF_SGB); ld = 2048; cofs = 8192; act = 2; }
;     #pragma unroll
;     for (int bj = 0; bj < 2; ++bj)
;       #pragma unroll
;       for (int n = 0; n < 2; ++n) {
;         const int t = EPI_T(bj, n);
;         const float r = rs[t];
;         u16* drow = dst + (size_t)t * ld - cofs;
;         #pragma unroll
;         for (int ai = 0; ai < 2; ++ai)
;           #pragma unroll
;           for (int m = 0; m < 4; ++m) {
;             float v[4];
;             #pragma unroll
;             for (int j = 0; j < 4; ++j) {
;               v[j] = acc[ai][bj][m][n][j] * r;
;               if (act == 2) v[j] = sigm(v[j]);
;             }
;             if (act == 2) {
;               *reinterpret_cast<unsigned*>(reinterpret_cast<unsigned char*>(dst) + (size_t)t * 2048 + (EPI_F(ai, m) - cofs)) =
;                   pk4_u8(v[0], v[1], v[2], v[3]);
.LBB0_167:
	s_or_b64 exec, exec, s[66:67]
	v_and_b32_e32 v130, 15, v194
	v_lshrrev_b32_e32 v131, 1, v194
	v_and_b32_e32 v131, 0x60, v131
	v_add3_u32 v132, s72, v130, v131
	v_lshlrev_b32_e32 v133, 2, v132
	global_load_dword v136, v133, s[30:31]
	global_load_dword v138, v133, s[30:31] offset:64
	global_load_dword v140, v133, s[30:31] offset:512
	global_load_dword v142, v133, s[30:31] offset:576
	v_bfe_u32 v134, v194, 4, 2
	v_lshrrev_b32_e32 v135, 2, v194
	v_and_b32_e32 v135, 0xffffffc0, v135
	s_mov_b64 s[66:67], s[42:43]
	s_movk_i32 s70, 0x1000
	s_mov_b32 s7, 0
	s_cmp_lt_i32 s94, 8
	s_cbranch_scc1 .Lp1e_bf16
	s_mov_b64 s[66:67], s[40:41]
	s_movk_i32 s7, 0x800
	s_cmp_lt_u32 s94, 16
	s_cbranch_scc1 .Lp1e_bf16
	s_mov_b64 s[66:67], s[44:45]
	s_movk_i32 s70, 0x800
	s_movk_i32 s7, 0x1000
	s_cmp_lt_u32 s94, 20
	s_cbranch_scc1 .Lp1e_bf16
	s_mov_b64 s[66:67], s[46:47]
	s_movk_i32 s7, 0x1400
	s_cmp_lt_u32 s94, 24
	s_cbranch_scc1 .Lp1e_bf16
	s_add_u32 s66, s30, 0x26000000
	s_addc_u32 s67, s31, 0
	s_movk_i32 s7, 0x1800
	s_cmp_lt_u32 s94, 32
	s_cbranch_scc1 .Lp1e_gate
	s_add_u32 s66, s30, 0x30000000
	s_addc_u32 s67, s31, 0
	s_movk_i32 s7, 0x2000
.Lp1e_gate:
	s_sub_i32 s24, s6, s7
	v_lshl_add_u32 v146, v134, 4, v135
	v_add_u32_e32 v146, s24, v146
	v_lshl_add_u32 v148, v132, 11, v146
	v_add_u32_e32 v149, 0x8000, v148
	v_add_u32_e32 v150, 0x40000, v148
	v_add_u32_e32 v151, 0x48000, v148
	s_waitcnt vmcnt(3)
	v_pk_mul_f32 v[124:125], v[124:125], v[136:137] op_sel_hi:[1,0]
	v_pk_mul_f32 v[126:127], v[126:127], v[136:137] op_sel_hi:[1,0]
	v_mul_f32_e32 v124, 0xbfb8aa3b, v124
	v_mul_f32_e32 v125, 0xbfb8aa3b, v125
	v_mul_f32_e32 v126, 0xbfb8aa3b, v126
	v_mul_f32_e32 v127, 0xbfb8aa3b, v127
	v_exp_f32_e32 v124, v124
	v_exp_f32_e32 v125, v125
	v_exp_f32_e32 v126, v126
	v_exp_f32_e32 v127, v127
	v_add_f32_e32 v124, 1.0, v124
	v_add_f32_e32 v125, 1.0, v125
	v_add_f32_e32 v126, 1.0, v126
	v_add_f32_e32 v127, 1.0, v127
	v_rcp_f32_e64 v124, v124 clamp
	v_rcp_f32_e64 v125, v125 clamp
	v_rcp_f32_e64 v126, v126 clamp
	v_rcp_f32_e64 v127, v127 clamp
	v_mul_f32_e32 v124, 0x437f0000, v124
	v_mul_f32_e32 v125, 0x437f0000, v125
	v_mul_f32_e32 v126, 0x437f0000, v126
	v_mul_f32_e32 v127, 0x437f0000, v127
	v_rndne_f32_e32 v124, v124
	v_rndne_f32_e32 v125, v125
	v_rndne_f32_e32 v126, v126
	v_rndne_f32_e32 v127, v127
	v_cvt_u32_f32_e32 v124, v124
	v_cvt_u32_f32_e32 v125, v125
	v_cvt_u32_f32_sdwa v126, v126 dst_sel:WORD_1 dst_unused:UNUSED_PAD src0_sel:DWORD
	v_cvt_u32_f32_sdwa v127, v127 dst_sel:BYTE_3 dst_unused:UNUSED_PAD src0_sel:DWORD
	v_lshl_or_b32 v160, v125, 8, v124
	v_or3_b32 v160, v160, v126, v127
	v_pk_mul_f32 v[120:121], v[120:121], v[136:137] op_sel_hi:[1,0]
	v_pk_mul_f32 v[122:123], v[122:123], v[136:137] op_sel_hi:[1,0]
	v_mul_f32_e32 v120, 0xbfb8aa3b, v120
	v_mul_f32_e32 v121, 0xbfb8aa3b, v121
	v_mul_f32_e32 v122, 0xbfb8aa3b, v122
	v_mul_f32_e32 v123, 0xbfb8aa3b, v123
	v_exp_f32_e32 v120, v120
	v_exp_f32_e32 v121, v121
	v_exp_f32_e32 v122, v122
	v_exp_f32_e32 v123, v123
	v_add_f32_e32 v120, 1.0, v120
	v_add_f32_e32 v121, 1.0, v121
	v_add_f32_e32 v122, 1.0, v122
	v_add_f32_e32 v123, 1.0, v123
	v_rcp_f32_e64 v120, v120 clamp
	v_rcp_f32_e64 v121, v121 clamp
	v_rcp_f32_e64 v122, v122 clamp
	v_rcp_f32_e64 v123, v123 clamp
	v_mul_f32_e32 v120, 0x437f0000, v120
	v_mul_f32_e32 v121, 0x437f0000, v121
	v_mul_f32_e32 v122, 0x437f0000, v122
	v_mul_f32_e32 v123, 0x437f0000, v123
	v_rndne_f32_e32 v120, v120
	v_rndne_f32_e32 v121, v121
	v_rndne_f32_e32 v122, v122
	v_rndne_f32_e32 v123, v123
	v_cvt_u32_f32_e32 v120, v120
	v_cvt_u32_f32_e32 v121, v121
	v_cvt_u32_f32_sdwa v122, v122 dst_sel:WORD_1 dst_unused:UNUSED_PAD src0_sel:DWORD
	v_cvt_u32_f32_sdwa v123, v123 dst_sel:BYTE_3 dst_unused:UNUSED_PAD src0_sel:DWORD
	v_lshl_or_b32 v161, v121, 8, v120
	v_or3_b32 v161, v161, v122, v123
	v_pk_mul_f32 v[116:117], v[116:117], v[136:137] op_sel_hi:[1,0]
	v_pk_mul_f32 v[118:119], v[118:119], v[136:137] op_sel_hi:[1,0]
	v_mul_f32_e32 v116, 0xbfb8aa3b, v116
	v_mul_f32_e32 v117, 0xbfb8aa3b, v117
	v_mul_f32_e32 v118, 0xbfb8aa3b, v118
	v_mul_f32_e32 v119, 0xbfb8aa3b, v119
	v_exp_f32_e32 v116, v116
	v_exp_f32_e32 v117, v117
	v_exp_f32_e32 v118, v118
	v_exp_f32_e32 v119, v119
	v_add_f32_e32 v116, 1.0, v116
	v_add_f32_e32 v117, 1.0, v117
	v_add_f32_e32 v118, 1.0, v118
	v_add_f32_e32 v119, 1.0, v119
	v_rcp_f32_e64 v116, v116 clamp
	v_rcp_f32_e64 v117, v117 clamp
	v_rcp_f32_e64 v118, v118 clamp
	v_rcp_f32_e64 v119, v119 clamp
	v_mul_f32_e32 v116, 0x437f0000, v116
	v_mul_f32_e32 v117, 0x437f0000, v117
	v_mul_f32_e32 v118, 0x437f0000, v118
	v_mul_f32_e32 v119, 0x437f0000, v119
	v_rndne_f32_e32 v116, v116
	v_rndne_f32_e32 v117, v117
	v_rndne_f32_e32 v118, v118
	v_rndne_f32_e32 v119, v119
	v_cvt_u32_f32_e32 v116, v116
	v_cvt_u32_f32_e32 v117, v117
	v_cvt_u32_f32_sdwa v118, v118 dst_sel:WORD_1 dst_unused:UNUSED_PAD src0_sel:DWORD
	v_cvt_u32_f32_sdwa v119, v119 dst_sel:BYTE_3 dst_unused:UNUSED_PAD src0_sel:DWORD
	v_lshl_or_b32 v162, v117, 8, v116
	v_or3_b32 v162, v162, v118, v119
	v_pk_mul_f32 v[112:113], v[112:113], v[136:137] op_sel_hi:[1,0]
	v_pk_mul_f32 v[114:115], v[114:115], v[136:137] op_sel_hi:[1,0]
	v_mul_f32_e32 v112, 0xbfb8aa3b, v112
	v_mul_f32_e32 v113, 0xbfb8aa3b, v113
	v_mul_f32_e32 v114, 0xbfb8aa3b, v114
	v_mul_f32_e32 v115, 0xbfb8aa3b, v115
	v_exp_f32_e32 v112, v112
	v_exp_f32_e32 v113, v113
	v_exp_f32_e32 v114, v114
	v_exp_f32_e32 v115, v115
	v_add_f32_e32 v112, 1.0, v112
	v_add_f32_e32 v113, 1.0, v113
	v_add_f32_e32 v114, 1.0, v114
	v_add_f32_e32 v115, 1.0, v115
	v_rcp_f32_e64 v112, v112 clamp
	v_rcp_f32_e64 v113, v113 clamp
	v_rcp_f32_e64 v114, v114 clamp
	v_rcp_f32_e64 v115, v115 clamp
; __device__ __forceinline__ float sigm(float x) {
;   return __builtin_amdgcn_rcpf(1.f + __builtin_amdgcn_exp2f(-1.44269504f * x));
; }
; __device__ __forceinline__ unsigned pk4_u8(float a, float b, float c, float d) {
;   const unsigned qa = (unsigned)__builtin_rintf(fminf(fmaxf(a, 0.f), 1.f) * 255.f);
;   const unsigned qb = (unsigned)__builtin_rintf(fminf(fmaxf(b, 0.f), 1.f) * 255.f);
;   const unsigned qc = (unsigned)__builtin_rintf(fminf(fmaxf(c, 0.f), 1.f) * 255.f);
;   const unsigned qd = (unsigned)__builtin_rintf(fminf(fmaxf(d, 0.f), 1.f) * 255.f);
;   return qa | (qb << 8) | (qc << 16) | (qd << 24);
; __device__ void phase1(const Params& p) {
;     ...
;             float v[4];
;             #pragma unroll
;             for (int j = 0; j < 4; ++j) {
;               v[j] = acc[ai][bj][m][n][j] * r;
;               if (act == 2) v[j] = sigm(v[j]);
;             }
;             if (act == 2) {
;               *reinterpret_cast<unsigned*>(reinterpret_cast<unsigned char*>(dst) + (size_t)t * 2048 + (EPI_F(ai, m) - cofs)) =
;                   pk4_u8(v[0], v[1], v[2], v[3]);
	v_mul_f32_e32 v112, 0x437f0000, v112
	v_mul_f32_e32 v113, 0x437f0000, v113
	v_mul_f32_e32 v114, 0x437f0000, v114
	v_mul_f32_e32 v115, 0x437f0000, v115
	v_rndne_f32_e32 v112, v112
	v_rndne_f32_e32 v113, v113
	v_rndne_f32_e32 v114, v114
	v_rndne_f32_e32 v115, v115
	v_cvt_u32_f32_e32 v112, v112
	v_cvt_u32_f32_e32 v113, v113
	v_cvt_u32_f32_sdwa v114, v114 dst_sel:WORD_1 dst_unused:UNUSED_PAD src0_sel:DWORD
	v_cvt_u32_f32_sdwa v115, v115 dst_sel:BYTE_3 dst_unused:UNUSED_PAD src0_sel:DWORD
	v_lshl_or_b32 v163, v113, 8, v112
	v_or3_b32 v163, v163, v114, v115
	s_nop 1
	v_permlane16_swap_b32 v160, v161
	v_permlane16_swap_b32 v162, v163
	s_nop 1
	v_permlane32_swap_b32 v160, v162
	v_permlane32_swap_b32 v161, v163
	global_store_dwordx4 v148, v[160:163], s[66:67]
	v_pk_mul_f32 v[108:109], v[108:109], v[136:137] op_sel_hi:[1,0]
	v_pk_mul_f32 v[110:111], v[110:111], v[136:137] op_sel_hi:[1,0]
	v_mul_f32_e32 v108, 0xbfb8aa3b, v108
	v_mul_f32_e32 v109, 0xbfb8aa3b, v109
	v_mul_f32_e32 v110, 0xbfb8aa3b, v110
	v_mul_f32_e32 v111, 0xbfb8aa3b, v111
	v_exp_f32_e32 v108, v108
	v_exp_f32_e32 v109, v109
	v_exp_f32_e32 v110, v110
	v_exp_f32_e32 v111, v111
	v_add_f32_e32 v108, 1.0, v108
	v_add_f32_e32 v109, 1.0, v109
	v_add_f32_e32 v110, 1.0, v110
	v_add_f32_e32 v111, 1.0, v111
	v_rcp_f32_e64 v108, v108 clamp
	v_rcp_f32_e64 v109, v109 clamp
	v_rcp_f32_e64 v110, v110 clamp
	v_rcp_f32_e64 v111, v111 clamp
	v_mul_f32_e32 v108, 0x437f0000, v108
	v_mul_f32_e32 v109, 0x437f0000, v109
	v_mul_f32_e32 v110, 0x437f0000, v110
	v_mul_f32_e32 v111, 0x437f0000, v111
	v_rndne_f32_e32 v108, v108
	v_rndne_f32_e32 v109, v109
	v_rndne_f32_e32 v110, v110
	v_rndne_f32_e32 v111, v111
	v_cvt_u32_f32_e32 v108, v108
	v_cvt_u32_f32_e32 v109, v109
	v_cvt_u32_f32_sdwa v110, v110 dst_sel:WORD_1 dst_unused:UNUSED_PAD src0_sel:DWORD
	v_cvt_u32_f32_sdwa v111, v111 dst_sel:BYTE_3 dst_unused:UNUSED_PAD src0_sel:DWORD
	v_lshl_or_b32 v164, v109, 8, v108
	v_or3_b32 v164, v164, v110, v111
	v_pk_mul_f32 v[104:105], v[104:105], v[136:137] op_sel_hi:[1,0]
	v_pk_mul_f32 v[106:107], v[106:107], v[136:137] op_sel_hi:[1,0]
	v_mul_f32_e32 v104, 0xbfb8aa3b, v104
	v_mul_f32_e32 v105, 0xbfb8aa3b, v105
	v_mul_f32_e32 v106, 0xbfb8aa3b, v106
	v_mul_f32_e32 v107, 0xbfb8aa3b, v107
	v_exp_f32_e32 v104, v104
	v_exp_f32_e32 v105, v105
	v_exp_f32_e32 v106, v106
	v_exp_f32_e32 v107, v107
	v_add_f32_e32 v104, 1.0, v104
	v_add_f32_e32 v105, 1.0, v105
	v_add_f32_e32 v106, 1.0, v106
	v_add_f32_e32 v107, 1.0, v107
	v_rcp_f32_e64 v104, v104 clamp
	v_rcp_f32_e64 v105, v105 clamp
	v_rcp_f32_e64 v106, v106 clamp
	v_rcp_f32_e64 v107, v107 clamp
	v_mul_f32_e32 v104, 0x437f0000, v104
	v_mul_f32_e32 v105, 0x437f0000, v105
	v_mul_f32_e32 v106, 0x437f0000, v106
	v_mul_f32_e32 v107, 0x437f0000, v107
	v_rndne_f32_e32 v104, v104
	v_rndne_f32_e32 v105, v105
	v_rndne_f32_e32 v106, v106
	v_rndne_f32_e32 v107, v107
	v_cvt_u32_f32_e32 v104, v104
	v_cvt_u32_f32_e32 v105, v105
	v_cvt_u32_f32_sdwa v106, v106 dst_sel:WORD_1 dst_unused:UNUSED_PAD src0_sel:DWORD
	v_cvt_u32_f32_sdwa v107, v107 dst_sel:BYTE_3 dst_unused:UNUSED_PAD src0_sel:DWORD
	v_lshl_or_b32 v165, v105, 8, v104
	v_or3_b32 v165, v165, v106, v107
	v_pk_mul_f32 v[100:101], v[100:101], v[136:137] op_sel_hi:[1,0]
	v_pk_mul_f32 v[102:103], v[102:103], v[136:137] op_sel_hi:[1,0]
	v_mul_f32_e32 v100, 0xbfb8aa3b, v100
	v_mul_f32_e32 v101, 0xbfb8aa3b, v101
	v_mul_f32_e32 v102, 0xbfb8aa3b, v102
	v_mul_f32_e32 v103, 0xbfb8aa3b, v103
	v_exp_f32_e32 v100, v100
	v_exp_f32_e32 v101, v101
	v_exp_f32_e32 v102, v102
	v_exp_f32_e32 v103, v103
	v_add_f32_e32 v100, 1.0, v100
	v_add_f32_e32 v101, 1.0, v101
	v_add_f32_e32 v102, 1.0, v102
	v_add_f32_e32 v103, 1.0, v103
	v_rcp_f32_e64 v100, v100 clamp
	v_rcp_f32_e64 v101, v101 clamp
	v_rcp_f32_e64 v102, v102 clamp
	v_rcp_f32_e64 v103, v103 clamp
	v_mul_f32_e32 v100, 0x437f0000, v100
	v_mul_f32_e32 v101, 0x437f0000, v101
	v_mul_f32_e32 v102, 0x437f0000, v102
	v_mul_f32_e32 v103, 0x437f0000, v103
	v_rndne_f32_e32 v100, v100
	v_rndne_f32_e32 v101, v101
	v_rndne_f32_e32 v102, v102
	v_rndne_f32_e32 v103, v103
	v_cvt_u32_f32_e32 v100, v100
	v_cvt_u32_f32_e32 v101, v101
	v_cvt_u32_f32_sdwa v102, v102 dst_sel:WORD_1 dst_unused:UNUSED_PAD src0_sel:DWORD
	v_cvt_u32_f32_sdwa v103, v103 dst_sel:BYTE_3 dst_unused:UNUSED_PAD src0_sel:DWORD
	v_lshl_or_b32 v166, v101, 8, v100
	v_or3_b32 v166, v166, v102, v103
	v_pk_mul_f32 v[96:97], v[96:97], v[136:137] op_sel_hi:[1,0]
	v_pk_mul_f32 v[98:99], v[98:99], v[136:137] op_sel_hi:[1,0]
	v_mul_f32_e32 v96, 0xbfb8aa3b, v96
	v_mul_f32_e32 v97, 0xbfb8aa3b, v97
	v_mul_f32_e32 v98, 0xbfb8aa3b, v98
	v_mul_f32_e32 v99, 0xbfb8aa3b, v99
	v_exp_f32_e32 v96, v96
	v_exp_f32_e32 v97, v97
	v_exp_f32_e32 v98, v98
	v_exp_f32_e32 v99, v99
	v_add_f32_e32 v96, 1.0, v96
	v_add_f32_e32 v97, 1.0, v97
	v_add_f32_e32 v98, 1.0, v98
	v_add_f32_e32 v99, 1.0, v99
	v_rcp_f32_e64 v96, v96 clamp
	v_rcp_f32_e64 v97, v97 clamp
	v_rcp_f32_e64 v98, v98 clamp
	v_rcp_f32_e64 v99, v99 clamp
	v_mul_f32_e32 v96, 0x437f0000, v96
	v_mul_f32_e32 v97, 0x437f0000, v97
	v_mul_f32_e32 v98, 0x437f0000, v98
	v_mul_f32_e32 v99, 0x437f0000, v99
	v_rndne_f32_e32 v96, v96
	v_rndne_f32_e32 v97, v97
	v_rndne_f32_e32 v98, v98
	v_rndne_f32_e32 v99, v99
	v_cvt_u32_f32_e32 v96, v96
	v_cvt_u32_f32_e32 v97, v97
	v_cvt_u32_f32_sdwa v98, v98 dst_sel:WORD_1 dst_unused:UNUSED_PAD src0_sel:DWORD
	v_cvt_u32_f32_sdwa v99, v99 dst_sel:BYTE_3 dst_unused:UNUSED_PAD src0_sel:DWORD
	v_lshl_or_b32 v167, v97, 8, v96
	v_or3_b32 v167, v167, v98, v99
	s_nop 1
	v_permlane16_swap_b32 v164, v165
	v_permlane16_swap_b32 v166, v167
	s_nop 1
	v_permlane32_swap_b32 v164, v166
	v_permlane32_swap_b32 v165, v167
	global_store_dwordx4 v148, v[164:167], s[66:67] offset:128
	s_waitcnt vmcnt(4)
; __device__ __forceinline__ float sigm(float x) {
;   return __builtin_amdgcn_rcpf(1.f + __builtin_amdgcn_exp2f(-1.44269504f * x));
; }
; __device__ __forceinline__ unsigned pk4_u8(float a, float b, float c, float d) {
;   const unsigned qa = (unsigned)__builtin_rintf(fminf(fmaxf(a, 0.f), 1.f) * 255.f);
;   const unsigned qb = (unsigned)__builtin_rintf(fminf(fmaxf(b, 0.f), 1.f) * 255.f);
;   const unsigned qc = (unsigned)__builtin_rintf(fminf(fmaxf(c, 0.f), 1.f) * 255.f);
;   const unsigned qd = (unsigned)__builtin_rintf(fminf(fmaxf(d, 0.f), 1.f) * 255.f);
;   return qa | (qb << 8) | (qc << 16) | (qd << 24);
; __device__ void phase1(const Params& p) {
;     ...
;             float v[4];
;             #pragma unroll
;             for (int j = 0; j < 4; ++j) {
;               v[j] = acc[ai][bj][m][n][j] * r;
;               if (act == 2) v[j] = sigm(v[j]);
;             }
;             if (act == 2) {
;               *reinterpret_cast<unsigned*>(reinterpret_cast<unsigned char*>(dst) + (size_t)t * 2048 + (EPI_F(ai, m) - cofs)) =
;                   pk4_u8(v[0], v[1], v[2], v[3]);
	v_pk_mul_f32 v[92:93], v[92:93], v[138:139] op_sel_hi:[1,0]
	v_pk_mul_f32 v[94:95], v[94:95], v[138:139] op_sel_hi:[1,0]
	v_mul_f32_e32 v92, 0xbfb8aa3b, v92
	v_mul_f32_e32 v93, 0xbfb8aa3b, v93
	v_mul_f32_e32 v94, 0xbfb8aa3b, v94
	v_mul_f32_e32 v95, 0xbfb8aa3b, v95
	v_exp_f32_e32 v92, v92
	v_exp_f32_e32 v93, v93
	v_exp_f32_e32 v94, v94
	v_exp_f32_e32 v95, v95
	v_add_f32_e32 v92, 1.0, v92
	v_add_f32_e32 v93, 1.0, v93
	v_add_f32_e32 v94, 1.0, v94
	v_add_f32_e32 v95, 1.0, v95
	v_rcp_f32_e64 v92, v92 clamp
	v_rcp_f32_e64 v93, v93 clamp
	v_rcp_f32_e64 v94, v94 clamp
	v_rcp_f32_e64 v95, v95 clamp
	v_mul_f32_e32 v92, 0x437f0000, v92
	v_mul_f32_e32 v93, 0x437f0000, v93
	v_mul_f32_e32 v94, 0x437f0000, v94
	v_mul_f32_e32 v95, 0x437f0000, v95
	v_rndne_f32_e32 v92, v92
	v_rndne_f32_e32 v93, v93
	v_rndne_f32_e32 v94, v94
	v_rndne_f32_e32 v95, v95
	v_cvt_u32_f32_e32 v92, v92
	v_cvt_u32_f32_e32 v93, v93
	v_cvt_u32_f32_sdwa v94, v94 dst_sel:WORD_1 dst_unused:UNUSED_PAD src0_sel:DWORD
	v_cvt_u32_f32_sdwa v95, v95 dst_sel:BYTE_3 dst_unused:UNUSED_PAD src0_sel:DWORD
	v_lshl_or_b32 v168, v93, 8, v92
	v_or3_b32 v168, v168, v94, v95
	v_pk_mul_f32 v[88:89], v[88:89], v[138:139] op_sel_hi:[1,0]
	v_pk_mul_f32 v[90:91], v[90:91], v[138:139] op_sel_hi:[1,0]
	v_mul_f32_e32 v88, 0xbfb8aa3b, v88
	v_mul_f32_e32 v89, 0xbfb8aa3b, v89
	v_mul_f32_e32 v90, 0xbfb8aa3b, v90
	v_mul_f32_e32 v91, 0xbfb8aa3b, v91
	v_exp_f32_e32 v88, v88
	v_exp_f32_e32 v89, v89
	v_exp_f32_e32 v90, v90
	v_exp_f32_e32 v91, v91
	v_add_f32_e32 v88, 1.0, v88
	v_add_f32_e32 v89, 1.0, v89
	v_add_f32_e32 v90, 1.0, v90
	v_add_f32_e32 v91, 1.0, v91
	v_rcp_f32_e64 v88, v88 clamp
	v_rcp_f32_e64 v89, v89 clamp
	v_rcp_f32_e64 v90, v90 clamp
	v_rcp_f32_e64 v91, v91 clamp
	v_mul_f32_e32 v88, 0x437f0000, v88
	v_mul_f32_e32 v89, 0x437f0000, v89
	v_mul_f32_e32 v90, 0x437f0000, v90
	v_mul_f32_e32 v91, 0x437f0000, v91
	v_rndne_f32_e32 v88, v88
	v_rndne_f32_e32 v89, v89
	v_rndne_f32_e32 v90, v90
	v_rndne_f32_e32 v91, v91
	v_cvt_u32_f32_e32 v88, v88
	v_cvt_u32_f32_e32 v89, v89
	v_cvt_u32_f32_sdwa v90, v90 dst_sel:WORD_1 dst_unused:UNUSED_PAD src0_sel:DWORD
	v_cvt_u32_f32_sdwa v91, v91 dst_sel:BYTE_3 dst_unused:UNUSED_PAD src0_sel:DWORD
	v_lshl_or_b32 v169, v89, 8, v88
	v_or3_b32 v169, v169, v90, v91
	v_pk_mul_f32 v[84:85], v[84:85], v[138:139] op_sel_hi:[1,0]
	v_pk_mul_f32 v[86:87], v[86:87], v[138:139] op_sel_hi:[1,0]
	v_mul_f32_e32 v84, 0xbfb8aa3b, v84
	v_mul_f32_e32 v85, 0xbfb8aa3b, v85
	v_mul_f32_e32 v86, 0xbfb8aa3b, v86
	v_mul_f32_e32 v87, 0xbfb8aa3b, v87
	v_exp_f32_e32 v84, v84
	v_exp_f32_e32 v85, v85
	v_exp_f32_e32 v86, v86
	v_exp_f32_e32 v87, v87
	v_add_f32_e32 v84, 1.0, v84
	v_add_f32_e32 v85, 1.0, v85
	v_add_f32_e32 v86, 1.0, v86
	v_add_f32_e32 v87, 1.0, v87
	v_rcp_f32_e64 v84, v84 clamp
	v_rcp_f32_e64 v85, v85 clamp
	v_rcp_f32_e64 v86, v86 clamp
	v_rcp_f32_e64 v87, v87 clamp
	v_mul_f32_e32 v84, 0x437f0000, v84
	v_mul_f32_e32 v85, 0x437f0000, v85
	v_mul_f32_e32 v86, 0x437f0000, v86
	v_mul_f32_e32 v87, 0x437f0000, v87
	v_rndne_f32_e32 v84, v84
	v_rndne_f32_e32 v85, v85
	v_rndne_f32_e32 v86, v86
	v_rndne_f32_e32 v87, v87
	v_cvt_u32_f32_e32 v84, v84
	v_cvt_u32_f32_e32 v85, v85
	v_cvt_u32_f32_sdwa v86, v86 dst_sel:WORD_1 dst_unused:UNUSED_PAD src0_sel:DWORD
	v_cvt_u32_f32_sdwa v87, v87 dst_sel:BYTE_3 dst_unused:UNUSED_PAD src0_sel:DWORD
	v_lshl_or_b32 v170, v85, 8, v84
	v_or3_b32 v170, v170, v86, v87
	v_pk_mul_f32 v[80:81], v[80:81], v[138:139] op_sel_hi:[1,0]
	v_pk_mul_f32 v[82:83], v[82:83], v[138:139] op_sel_hi:[1,0]
	v_mul_f32_e32 v80, 0xbfb8aa3b, v80
	v_mul_f32_e32 v81, 0xbfb8aa3b, v81
	v_mul_f32_e32 v82, 0xbfb8aa3b, v82
	v_mul_f32_e32 v83, 0xbfb8aa3b, v83
	v_exp_f32_e32 v80, v80
	v_exp_f32_e32 v81, v81
	v_exp_f32_e32 v82, v82
	v_exp_f32_e32 v83, v83
	v_add_f32_e32 v80, 1.0, v80
	v_add_f32_e32 v81, 1.0, v81
	v_add_f32_e32 v82, 1.0, v82
	v_add_f32_e32 v83, 1.0, v83
	v_rcp_f32_e64 v80, v80 clamp
	v_rcp_f32_e64 v81, v81 clamp
	v_rcp_f32_e64 v82, v82 clamp
	v_rcp_f32_e64 v83, v83 clamp
	v_mul_f32_e32 v80, 0x437f0000, v80
	v_mul_f32_e32 v81, 0x437f0000, v81
	v_mul_f32_e32 v82, 0x437f0000, v82
	v_mul_f32_e32 v83, 0x437f0000, v83
	v_rndne_f32_e32 v80, v80
	v_rndne_f32_e32 v81, v81
	v_rndne_f32_e32 v82, v82
	v_rndne_f32_e32 v83, v83
	v_cvt_u32_f32_e32 v80, v80
	v_cvt_u32_f32_e32 v81, v81
	v_cvt_u32_f32_sdwa v82, v82 dst_sel:WORD_1 dst_unused:UNUSED_PAD src0_sel:DWORD
	v_cvt_u32_f32_sdwa v83, v83 dst_sel:BYTE_3 dst_unused:UNUSED_PAD src0_sel:DWORD
	v_lshl_or_b32 v171, v81, 8, v80
	v_or3_b32 v171, v171, v82, v83
	s_nop 1
	v_permlane16_swap_b32 v168, v169
	v_permlane16_swap_b32 v170, v171
	s_nop 1
	v_permlane32_swap_b32 v168, v170
	v_permlane32_swap_b32 v169, v171
	global_store_dwordx4 v149, v[168:171], s[66:67]
	v_pk_mul_f32 v[76:77], v[76:77], v[138:139] op_sel_hi:[1,0]
	v_pk_mul_f32 v[78:79], v[78:79], v[138:139] op_sel_hi:[1,0]
	v_mul_f32_e32 v76, 0xbfb8aa3b, v76
	v_mul_f32_e32 v77, 0xbfb8aa3b, v77
	v_mul_f32_e32 v78, 0xbfb8aa3b, v78
	v_mul_f32_e32 v79, 0xbfb8aa3b, v79
	v_exp_f32_e32 v76, v76
	v_exp_f32_e32 v77, v77
	v_exp_f32_e32 v78, v78
	v_exp_f32_e32 v79, v79
	v_add_f32_e32 v76, 1.0, v76
	v_add_f32_e32 v77, 1.0, v77
	v_add_f32_e32 v78, 1.0, v78
	v_add_f32_e32 v79, 1.0, v79
	v_rcp_f32_e64 v76, v76 clamp
	v_rcp_f32_e64 v77, v77 clamp
	v_rcp_f32_e64 v78, v78 clamp
	v_rcp_f32_e64 v79, v79 clamp
	v_mul_f32_e32 v76, 0x437f0000, v76
	v_mul_f32_e32 v77, 0x437f0000, v77
	v_mul_f32_e32 v78, 0x437f0000, v78
	v_mul_f32_e32 v79, 0x437f0000, v79
	v_rndne_f32_e32 v76, v76
	v_rndne_f32_e32 v77, v77
	v_rndne_f32_e32 v78, v78
	v_rndne_f32_e32 v79, v79
	v_cvt_u32_f32_e32 v76, v76
	v_cvt_u32_f32_e32 v77, v77
; __device__ __forceinline__ float sigm(float x) {
;   return __builtin_amdgcn_rcpf(1.f + __builtin_amdgcn_exp2f(-1.44269504f * x));
; }
; __device__ __forceinline__ unsigned pk4_u8(float a, float b, float c, float d) {
;   const unsigned qa = (unsigned)__builtin_rintf(fminf(fmaxf(a, 0.f), 1.f) * 255.f);
;   const unsigned qb = (unsigned)__builtin_rintf(fminf(fmaxf(b, 0.f), 1.f) * 255.f);
;   const unsigned qc = (unsigned)__builtin_rintf(fminf(fmaxf(c, 0.f), 1.f) * 255.f);
;   const unsigned qd = (unsigned)__builtin_rintf(fminf(fmaxf(d, 0.f), 1.f) * 255.f);
;   return qa | (qb << 8) | (qc << 16) | (qd << 24);
; __device__ void phase1(const Params& p) {
;     ...
;             float v[4];
;             #pragma unroll
;             for (int j = 0; j < 4; ++j) {
;               v[j] = acc[ai][bj][m][n][j] * r;
;               if (act == 2) v[j] = sigm(v[j]);
;             }
;             if (act == 2) {
;               *reinterpret_cast<unsigned*>(reinterpret_cast<unsigned char*>(dst) + (size_t)t * 2048 + (EPI_F(ai, m) - cofs)) =
;                   pk4_u8(v[0], v[1], v[2], v[3]);
	v_cvt_u32_f32_sdwa v78, v78 dst_sel:WORD_1 dst_unused:UNUSED_PAD src0_sel:DWORD
	v_cvt_u32_f32_sdwa v79, v79 dst_sel:BYTE_3 dst_unused:UNUSED_PAD src0_sel:DWORD
	v_lshl_or_b32 v172, v77, 8, v76
	v_or3_b32 v172, v172, v78, v79
	v_pk_mul_f32 v[72:73], v[72:73], v[138:139] op_sel_hi:[1,0]
	v_pk_mul_f32 v[74:75], v[74:75], v[138:139] op_sel_hi:[1,0]
	v_mul_f32_e32 v72, 0xbfb8aa3b, v72
	v_mul_f32_e32 v73, 0xbfb8aa3b, v73
	v_mul_f32_e32 v74, 0xbfb8aa3b, v74
	v_mul_f32_e32 v75, 0xbfb8aa3b, v75
	v_exp_f32_e32 v72, v72
	v_exp_f32_e32 v73, v73
	v_exp_f32_e32 v74, v74
	v_exp_f32_e32 v75, v75
	v_add_f32_e32 v72, 1.0, v72
	v_add_f32_e32 v73, 1.0, v73
	v_add_f32_e32 v74, 1.0, v74
	v_add_f32_e32 v75, 1.0, v75
	v_rcp_f32_e64 v72, v72 clamp
	v_rcp_f32_e64 v73, v73 clamp
	v_rcp_f32_e64 v74, v74 clamp
	v_rcp_f32_e64 v75, v75 clamp
	v_mul_f32_e32 v72, 0x437f0000, v72
	v_mul_f32_e32 v73, 0x437f0000, v73
	v_mul_f32_e32 v74, 0x437f0000, v74
	v_mul_f32_e32 v75, 0x437f0000, v75
	v_rndne_f32_e32 v72, v72
	v_rndne_f32_e32 v73, v73
	v_rndne_f32_e32 v74, v74
	v_rndne_f32_e32 v75, v75
	v_cvt_u32_f32_e32 v72, v72
	v_cvt_u32_f32_e32 v73, v73
	v_cvt_u32_f32_sdwa v74, v74 dst_sel:WORD_1 dst_unused:UNUSED_PAD src0_sel:DWORD
	v_cvt_u32_f32_sdwa v75, v75 dst_sel:BYTE_3 dst_unused:UNUSED_PAD src0_sel:DWORD
	v_lshl_or_b32 v173, v73, 8, v72
	v_or3_b32 v173, v173, v74, v75
	v_pk_mul_f32 v[68:69], v[68:69], v[138:139] op_sel_hi:[1,0]
	v_pk_mul_f32 v[70:71], v[70:71], v[138:139] op_sel_hi:[1,0]
	v_mul_f32_e32 v68, 0xbfb8aa3b, v68
	v_mul_f32_e32 v69, 0xbfb8aa3b, v69
	v_mul_f32_e32 v70, 0xbfb8aa3b, v70
	v_mul_f32_e32 v71, 0xbfb8aa3b, v71
	v_exp_f32_e32 v68, v68
	v_exp_f32_e32 v69, v69
	v_exp_f32_e32 v70, v70
	v_exp_f32_e32 v71, v71
	v_add_f32_e32 v68, 1.0, v68
	v_add_f32_e32 v69, 1.0, v69
	v_add_f32_e32 v70, 1.0, v70
	v_add_f32_e32 v71, 1.0, v71
	v_rcp_f32_e64 v68, v68 clamp
	v_rcp_f32_e64 v69, v69 clamp
	v_rcp_f32_e64 v70, v70 clamp
	v_rcp_f32_e64 v71, v71 clamp
	v_mul_f32_e32 v68, 0x437f0000, v68
	v_mul_f32_e32 v69, 0x437f0000, v69
	v_mul_f32_e32 v70, 0x437f0000, v70
	v_mul_f32_e32 v71, 0x437f0000, v71
	v_rndne_f32_e32 v68, v68
	v_rndne_f32_e32 v69, v69
	v_rndne_f32_e32 v70, v70
	v_rndne_f32_e32 v71, v71
	v_cvt_u32_f32_e32 v68, v68
	v_cvt_u32_f32_e32 v69, v69
	v_cvt_u32_f32_sdwa v70, v70 dst_sel:WORD_1 dst_unused:UNUSED_PAD src0_sel:DWORD
	v_cvt_u32_f32_sdwa v71, v71 dst_sel:BYTE_3 dst_unused:UNUSED_PAD src0_sel:DWORD
	v_lshl_or_b32 v174, v69, 8, v68
	v_or3_b32 v174, v174, v70, v71
	v_pk_mul_f32 v[64:65], v[64:65], v[138:139] op_sel_hi:[1,0]
	v_pk_mul_f32 v[66:67], v[66:67], v[138:139] op_sel_hi:[1,0]
	v_mul_f32_e32 v64, 0xbfb8aa3b, v64
	v_mul_f32_e32 v65, 0xbfb8aa3b, v65
	v_mul_f32_e32 v66, 0xbfb8aa3b, v66
	v_mul_f32_e32 v67, 0xbfb8aa3b, v67
	v_exp_f32_e32 v64, v64
	v_exp_f32_e32 v65, v65
	v_exp_f32_e32 v66, v66
	v_exp_f32_e32 v67, v67
	v_add_f32_e32 v64, 1.0, v64
	v_add_f32_e32 v65, 1.0, v65
	v_add_f32_e32 v66, 1.0, v66
	v_add_f32_e32 v67, 1.0, v67
	v_rcp_f32_e64 v64, v64 clamp
	v_rcp_f32_e64 v65, v65 clamp
	v_rcp_f32_e64 v66, v66 clamp
	v_rcp_f32_e64 v67, v67 clamp
	v_mul_f32_e32 v64, 0x437f0000, v64
	v_mul_f32_e32 v65, 0x437f0000, v65
	v_mul_f32_e32 v66, 0x437f0000, v66
	v_mul_f32_e32 v67, 0x437f0000, v67
	v_rndne_f32_e32 v64, v64
	v_rndne_f32_e32 v65, v65
	v_rndne_f32_e32 v66, v66
	v_rndne_f32_e32 v67, v67
	v_cvt_u32_f32_e32 v64, v64
	v_cvt_u32_f32_e32 v65, v65
	v_cvt_u32_f32_sdwa v66, v66 dst_sel:WORD_1 dst_unused:UNUSED_PAD src0_sel:DWORD
	v_cvt_u32_f32_sdwa v67, v67 dst_sel:BYTE_3 dst_unused:UNUSED_PAD src0_sel:DWORD
	v_lshl_or_b32 v175, v65, 8, v64
	v_or3_b32 v175, v175, v66, v67
	s_nop 1
	v_permlane16_swap_b32 v172, v173
	v_permlane16_swap_b32 v174, v175
	s_nop 1
	v_permlane32_swap_b32 v172, v174
	v_permlane32_swap_b32 v173, v175
	global_store_dwordx4 v149, v[172:175], s[66:67] offset:128
	s_waitcnt vmcnt(5)
	v_pk_mul_f32 v[60:61], v[60:61], v[140:141] op_sel_hi:[1,0]
	v_pk_mul_f32 v[62:63], v[62:63], v[140:141] op_sel_hi:[1,0]
	v_mul_f32_e32 v60, 0xbfb8aa3b, v60
	v_mul_f32_e32 v61, 0xbfb8aa3b, v61
	v_mul_f32_e32 v62, 0xbfb8aa3b, v62
	v_mul_f32_e32 v63, 0xbfb8aa3b, v63
	v_exp_f32_e32 v60, v60
	v_exp_f32_e32 v61, v61
	v_exp_f32_e32 v62, v62
	v_exp_f32_e32 v63, v63
	v_add_f32_e32 v60, 1.0, v60
	v_add_f32_e32 v61, 1.0, v61
	v_add_f32_e32 v62, 1.0, v62
	v_add_f32_e32 v63, 1.0, v63
	v_rcp_f32_e64 v60, v60 clamp
	v_rcp_f32_e64 v61, v61 clamp
	v_rcp_f32_e64 v62, v62 clamp
	v_rcp_f32_e64 v63, v63 clamp
	v_mul_f32_e32 v60, 0x437f0000, v60
	v_mul_f32_e32 v61, 0x437f0000, v61
	v_mul_f32_e32 v62, 0x437f0000, v62
	v_mul_f32_e32 v63, 0x437f0000, v63
	v_rndne_f32_e32 v60, v60
	v_rndne_f32_e32 v61, v61
	v_rndne_f32_e32 v62, v62
	v_rndne_f32_e32 v63, v63
	v_cvt_u32_f32_e32 v60, v60
	v_cvt_u32_f32_e32 v61, v61
	v_cvt_u32_f32_sdwa v62, v62 dst_sel:WORD_1 dst_unused:UNUSED_PAD src0_sel:DWORD
	v_cvt_u32_f32_sdwa v63, v63 dst_sel:BYTE_3 dst_unused:UNUSED_PAD src0_sel:DWORD
	v_lshl_or_b32 v176, v61, 8, v60
	v_or3_b32 v176, v176, v62, v63
	v_pk_mul_f32 v[56:57], v[56:57], v[140:141] op_sel_hi:[1,0]
	v_pk_mul_f32 v[58:59], v[58:59], v[140:141] op_sel_hi:[1,0]
	v_mul_f32_e32 v56, 0xbfb8aa3b, v56
	v_mul_f32_e32 v57, 0xbfb8aa3b, v57
	v_mul_f32_e32 v58, 0xbfb8aa3b, v58
	v_mul_f32_e32 v59, 0xbfb8aa3b, v59
	v_exp_f32_e32 v56, v56
	v_exp_f32_e32 v57, v57
	v_exp_f32_e32 v58, v58
	v_exp_f32_e32 v59, v59
	v_add_f32_e32 v56, 1.0, v56
	v_add_f32_e32 v57, 1.0, v57
	v_add_f32_e32 v58, 1.0, v58
	v_add_f32_e32 v59, 1.0, v59
	v_rcp_f32_e64 v56, v56 clamp
	v_rcp_f32_e64 v57, v57 clamp
	v_rcp_f32_e64 v58, v58 clamp
	v_rcp_f32_e64 v59, v59 clamp
	v_mul_f32_e32 v56, 0x437f0000, v56
	v_mul_f32_e32 v57, 0x437f0000, v57
; __device__ __forceinline__ float sigm(float x) {
;   return __builtin_amdgcn_rcpf(1.f + __builtin_amdgcn_exp2f(-1.44269504f * x));
; }
; __device__ __forceinline__ unsigned pk4_u8(float a, float b, float c, float d) {
;   const unsigned qa = (unsigned)__builtin_rintf(fminf(fmaxf(a, 0.f), 1.f) * 255.f);
;   const unsigned qb = (unsigned)__builtin_rintf(fminf(fmaxf(b, 0.f), 1.f) * 255.f);
;   const unsigned qc = (unsigned)__builtin_rintf(fminf(fmaxf(c, 0.f), 1.f) * 255.f);
;   const unsigned qd = (unsigned)__builtin_rintf(fminf(fmaxf(d, 0.f), 1.f) * 255.f);
;   return qa | (qb << 8) | (qc << 16) | (qd << 24);
; __device__ void phase1(const Params& p) {
;     ...
;             float v[4];
;             #pragma unroll
;             for (int j = 0; j < 4; ++j) {
;               v[j] = acc[ai][bj][m][n][j] * r;
;               if (act == 2) v[j] = sigm(v[j]);
;             }
;             if (act == 2) {
;               *reinterpret_cast<unsigned*>(reinterpret_cast<unsigned char*>(dst) + (size_t)t * 2048 + (EPI_F(ai, m) - cofs)) =
;                   pk4_u8(v[0], v[1], v[2], v[3]);
	v_mul_f32_e32 v58, 0x437f0000, v58
	v_mul_f32_e32 v59, 0x437f0000, v59
	v_rndne_f32_e32 v56, v56
	v_rndne_f32_e32 v57, v57
	v_rndne_f32_e32 v58, v58
	v_rndne_f32_e32 v59, v59
	v_cvt_u32_f32_e32 v56, v56
	v_cvt_u32_f32_e32 v57, v57
	v_cvt_u32_f32_sdwa v58, v58 dst_sel:WORD_1 dst_unused:UNUSED_PAD src0_sel:DWORD
	v_cvt_u32_f32_sdwa v59, v59 dst_sel:BYTE_3 dst_unused:UNUSED_PAD src0_sel:DWORD
	v_lshl_or_b32 v177, v57, 8, v56
	v_or3_b32 v177, v177, v58, v59
	v_pk_mul_f32 v[52:53], v[52:53], v[140:141] op_sel_hi:[1,0]
	v_pk_mul_f32 v[54:55], v[54:55], v[140:141] op_sel_hi:[1,0]
	v_mul_f32_e32 v52, 0xbfb8aa3b, v52
	v_mul_f32_e32 v53, 0xbfb8aa3b, v53
	v_mul_f32_e32 v54, 0xbfb8aa3b, v54
	v_mul_f32_e32 v55, 0xbfb8aa3b, v55
	v_exp_f32_e32 v52, v52
	v_exp_f32_e32 v53, v53
	v_exp_f32_e32 v54, v54
	v_exp_f32_e32 v55, v55
	v_add_f32_e32 v52, 1.0, v52
	v_add_f32_e32 v53, 1.0, v53
	v_add_f32_e32 v54, 1.0, v54
	v_add_f32_e32 v55, 1.0, v55
	v_rcp_f32_e64 v52, v52 clamp
	v_rcp_f32_e64 v53, v53 clamp
	v_rcp_f32_e64 v54, v54 clamp
	v_rcp_f32_e64 v55, v55 clamp
	v_mul_f32_e32 v52, 0x437f0000, v52
	v_mul_f32_e32 v53, 0x437f0000, v53
	v_mul_f32_e32 v54, 0x437f0000, v54
	v_mul_f32_e32 v55, 0x437f0000, v55
	v_rndne_f32_e32 v52, v52
	v_rndne_f32_e32 v53, v53
	v_rndne_f32_e32 v54, v54
	v_rndne_f32_e32 v55, v55
	v_cvt_u32_f32_e32 v52, v52
	v_cvt_u32_f32_e32 v53, v53
	v_cvt_u32_f32_sdwa v54, v54 dst_sel:WORD_1 dst_unused:UNUSED_PAD src0_sel:DWORD
	v_cvt_u32_f32_sdwa v55, v55 dst_sel:BYTE_3 dst_unused:UNUSED_PAD src0_sel:DWORD
	v_lshl_or_b32 v178, v53, 8, v52
	v_or3_b32 v178, v178, v54, v55
	v_pk_mul_f32 v[48:49], v[48:49], v[140:141] op_sel_hi:[1,0]
	v_pk_mul_f32 v[50:51], v[50:51], v[140:141] op_sel_hi:[1,0]
	v_mul_f32_e32 v48, 0xbfb8aa3b, v48
	v_mul_f32_e32 v49, 0xbfb8aa3b, v49
	v_mul_f32_e32 v50, 0xbfb8aa3b, v50
	v_mul_f32_e32 v51, 0xbfb8aa3b, v51
	v_exp_f32_e32 v48, v48
	v_exp_f32_e32 v49, v49
	v_exp_f32_e32 v50, v50
	v_exp_f32_e32 v51, v51
	v_add_f32_e32 v48, 1.0, v48
	v_add_f32_e32 v49, 1.0, v49
	v_add_f32_e32 v50, 1.0, v50
	v_add_f32_e32 v51, 1.0, v51
	v_rcp_f32_e64 v48, v48 clamp
	v_rcp_f32_e64 v49, v49 clamp
	v_rcp_f32_e64 v50, v50 clamp
	v_rcp_f32_e64 v51, v51 clamp
	v_mul_f32_e32 v48, 0x437f0000, v48
	v_mul_f32_e32 v49, 0x437f0000, v49
	v_mul_f32_e32 v50, 0x437f0000, v50
	v_mul_f32_e32 v51, 0x437f0000, v51
	v_rndne_f32_e32 v48, v48
	v_rndne_f32_e32 v49, v49
	v_rndne_f32_e32 v50, v50
	v_rndne_f32_e32 v51, v51
	v_cvt_u32_f32_e32 v48, v48
	v_cvt_u32_f32_e32 v49, v49
	v_cvt_u32_f32_sdwa v50, v50 dst_sel:WORD_1 dst_unused:UNUSED_PAD src0_sel:DWORD
	v_cvt_u32_f32_sdwa v51, v51 dst_sel:BYTE_3 dst_unused:UNUSED_PAD src0_sel:DWORD
	v_lshl_or_b32 v179, v49, 8, v48
	v_or3_b32 v179, v179, v50, v51
	s_nop 1
	v_permlane16_swap_b32 v176, v177
	v_permlane16_swap_b32 v178, v179
	s_nop 1
	v_permlane32_swap_b32 v176, v178
	v_permlane32_swap_b32 v177, v179
	global_store_dwordx4 v150, v[176:179], s[66:67]
	v_pk_mul_f32 v[44:45], v[44:45], v[140:141] op_sel_hi:[1,0]
	v_pk_mul_f32 v[46:47], v[46:47], v[140:141] op_sel_hi:[1,0]
	v_mul_f32_e32 v44, 0xbfb8aa3b, v44
	v_mul_f32_e32 v45, 0xbfb8aa3b, v45
	v_mul_f32_e32 v46, 0xbfb8aa3b, v46
	v_mul_f32_e32 v47, 0xbfb8aa3b, v47
	v_exp_f32_e32 v44, v44
	v_exp_f32_e32 v45, v45
	v_exp_f32_e32 v46, v46
	v_exp_f32_e32 v47, v47
	v_add_f32_e32 v44, 1.0, v44
	v_add_f32_e32 v45, 1.0, v45
	v_add_f32_e32 v46, 1.0, v46
	v_add_f32_e32 v47, 1.0, v47
	v_rcp_f32_e64 v44, v44 clamp
	v_rcp_f32_e64 v45, v45 clamp
	v_rcp_f32_e64 v46, v46 clamp
	v_rcp_f32_e64 v47, v47 clamp
	v_mul_f32_e32 v44, 0x437f0000, v44
	v_mul_f32_e32 v45, 0x437f0000, v45
	v_mul_f32_e32 v46, 0x437f0000, v46
	v_mul_f32_e32 v47, 0x437f0000, v47
	v_rndne_f32_e32 v44, v44
	v_rndne_f32_e32 v45, v45
	v_rndne_f32_e32 v46, v46
	v_rndne_f32_e32 v47, v47
	v_cvt_u32_f32_e32 v44, v44
	v_cvt_u32_f32_e32 v45, v45
	v_cvt_u32_f32_sdwa v46, v46 dst_sel:WORD_1 dst_unused:UNUSED_PAD src0_sel:DWORD
	v_cvt_u32_f32_sdwa v47, v47 dst_sel:BYTE_3 dst_unused:UNUSED_PAD src0_sel:DWORD
	v_lshl_or_b32 v180, v45, 8, v44
	v_or3_b32 v180, v180, v46, v47
	v_pk_mul_f32 v[40:41], v[40:41], v[140:141] op_sel_hi:[1,0]
	v_pk_mul_f32 v[42:43], v[42:43], v[140:141] op_sel_hi:[1,0]
	v_mul_f32_e32 v40, 0xbfb8aa3b, v40
	v_mul_f32_e32 v41, 0xbfb8aa3b, v41
	v_mul_f32_e32 v42, 0xbfb8aa3b, v42
	v_mul_f32_e32 v43, 0xbfb8aa3b, v43
	v_exp_f32_e32 v40, v40
	v_exp_f32_e32 v41, v41
	v_exp_f32_e32 v42, v42
	v_exp_f32_e32 v43, v43
	v_add_f32_e32 v40, 1.0, v40
	v_add_f32_e32 v41, 1.0, v41
	v_add_f32_e32 v42, 1.0, v42
	v_add_f32_e32 v43, 1.0, v43
	v_rcp_f32_e64 v40, v40 clamp
	v_rcp_f32_e64 v41, v41 clamp
	v_rcp_f32_e64 v42, v42 clamp
	v_rcp_f32_e64 v43, v43 clamp
	v_mul_f32_e32 v40, 0x437f0000, v40
	v_mul_f32_e32 v41, 0x437f0000, v41
	v_mul_f32_e32 v42, 0x437f0000, v42
	v_mul_f32_e32 v43, 0x437f0000, v43
	v_rndne_f32_e32 v40, v40
	v_rndne_f32_e32 v41, v41
	v_rndne_f32_e32 v42, v42
	v_rndne_f32_e32 v43, v43
	v_cvt_u32_f32_e32 v40, v40
	v_cvt_u32_f32_e32 v41, v41
	v_cvt_u32_f32_sdwa v42, v42 dst_sel:WORD_1 dst_unused:UNUSED_PAD src0_sel:DWORD
	v_cvt_u32_f32_sdwa v43, v43 dst_sel:BYTE_3 dst_unused:UNUSED_PAD src0_sel:DWORD
	v_lshl_or_b32 v181, v41, 8, v40
	v_or3_b32 v181, v181, v42, v43
	v_pk_mul_f32 v[36:37], v[36:37], v[140:141] op_sel_hi:[1,0]
	v_pk_mul_f32 v[38:39], v[38:39], v[140:141] op_sel_hi:[1,0]
	v_mul_f32_e32 v36, 0xbfb8aa3b, v36
	v_mul_f32_e32 v37, 0xbfb8aa3b, v37
	v_mul_f32_e32 v38, 0xbfb8aa3b, v38
	v_mul_f32_e32 v39, 0xbfb8aa3b, v39
	v_exp_f32_e32 v36, v36
	v_exp_f32_e32 v37, v37
	v_exp_f32_e32 v38, v38
	v_exp_f32_e32 v39, v39
	v_add_f32_e32 v36, 1.0, v36
	v_add_f32_e32 v37, 1.0, v37
	v_add_f32_e32 v38, 1.0, v38
; __device__ __forceinline__ float sigm(float x) {
;   return __builtin_amdgcn_rcpf(1.f + __builtin_amdgcn_exp2f(-1.44269504f * x));
; }
; __device__ __forceinline__ unsigned pk4_u8(float a, float b, float c, float d) {
;   const unsigned qa = (unsigned)__builtin_rintf(fminf(fmaxf(a, 0.f), 1.f) * 255.f);
;   const unsigned qb = (unsigned)__builtin_rintf(fminf(fmaxf(b, 0.f), 1.f) * 255.f);
;   const unsigned qc = (unsigned)__builtin_rintf(fminf(fmaxf(c, 0.f), 1.f) * 255.f);
;   const unsigned qd = (unsigned)__builtin_rintf(fminf(fmaxf(d, 0.f), 1.f) * 255.f);
;   return qa | (qb << 8) | (qc << 16) | (qd << 24);
; __device__ void phase1(const Params& p) {
;     ...
;             float v[4];
;             #pragma unroll
;             for (int j = 0; j < 4; ++j) {
;               v[j] = acc[ai][bj][m][n][j] * r;
;               if (act == 2) v[j] = sigm(v[j]);
;             }
;             if (act == 2) {
;               *reinterpret_cast<unsigned*>(reinterpret_cast<unsigned char*>(dst) + (size_t)t * 2048 + (EPI_F(ai, m) - cofs)) =
;                   pk4_u8(v[0], v[1], v[2], v[3]);
	v_add_f32_e32 v39, 1.0, v39
	v_rcp_f32_e64 v36, v36 clamp
	v_rcp_f32_e64 v37, v37 clamp
	v_rcp_f32_e64 v38, v38 clamp
	v_rcp_f32_e64 v39, v39 clamp
	v_mul_f32_e32 v36, 0x437f0000, v36
	v_mul_f32_e32 v37, 0x437f0000, v37
	v_mul_f32_e32 v38, 0x437f0000, v38
	v_mul_f32_e32 v39, 0x437f0000, v39
	v_rndne_f32_e32 v36, v36
	v_rndne_f32_e32 v37, v37
	v_rndne_f32_e32 v38, v38
	v_rndne_f32_e32 v39, v39
	v_cvt_u32_f32_e32 v36, v36
	v_cvt_u32_f32_e32 v37, v37
	v_cvt_u32_f32_sdwa v38, v38 dst_sel:WORD_1 dst_unused:UNUSED_PAD src0_sel:DWORD
	v_cvt_u32_f32_sdwa v39, v39 dst_sel:BYTE_3 dst_unused:UNUSED_PAD src0_sel:DWORD
	v_lshl_or_b32 v182, v37, 8, v36
	v_or3_b32 v182, v182, v38, v39
	v_pk_mul_f32 v[32:33], v[32:33], v[140:141] op_sel_hi:[1,0]
	v_pk_mul_f32 v[34:35], v[34:35], v[140:141] op_sel_hi:[1,0]
	v_mul_f32_e32 v32, 0xbfb8aa3b, v32
	v_mul_f32_e32 v33, 0xbfb8aa3b, v33
	v_mul_f32_e32 v34, 0xbfb8aa3b, v34
	v_mul_f32_e32 v35, 0xbfb8aa3b, v35
	v_exp_f32_e32 v32, v32
	v_exp_f32_e32 v33, v33
	v_exp_f32_e32 v34, v34
	v_exp_f32_e32 v35, v35
	v_add_f32_e32 v32, 1.0, v32
	v_add_f32_e32 v33, 1.0, v33
	v_add_f32_e32 v34, 1.0, v34
	v_add_f32_e32 v35, 1.0, v35
	v_rcp_f32_e64 v32, v32 clamp
	v_rcp_f32_e64 v33, v33 clamp
	v_rcp_f32_e64 v34, v34 clamp
	v_rcp_f32_e64 v35, v35 clamp
	v_mul_f32_e32 v32, 0x437f0000, v32
	v_mul_f32_e32 v33, 0x437f0000, v33
	v_mul_f32_e32 v34, 0x437f0000, v34
	v_mul_f32_e32 v35, 0x437f0000, v35
	v_rndne_f32_e32 v32, v32
	v_rndne_f32_e32 v33, v33
	v_rndne_f32_e32 v34, v34
	v_rndne_f32_e32 v35, v35
	v_cvt_u32_f32_e32 v32, v32
	v_cvt_u32_f32_e32 v33, v33
	v_cvt_u32_f32_sdwa v34, v34 dst_sel:WORD_1 dst_unused:UNUSED_PAD src0_sel:DWORD
	v_cvt_u32_f32_sdwa v35, v35 dst_sel:BYTE_3 dst_unused:UNUSED_PAD src0_sel:DWORD
	v_lshl_or_b32 v183, v33, 8, v32
	v_or3_b32 v183, v183, v34, v35
	s_nop 1
	v_permlane16_swap_b32 v180, v181
	v_permlane16_swap_b32 v182, v183
	s_nop 1
	v_permlane32_swap_b32 v180, v182
	v_permlane32_swap_b32 v181, v183
	global_store_dwordx4 v150, v[180:183], s[66:67] offset:128
	s_waitcnt vmcnt(6)
	v_pk_mul_f32 v[28:29], v[28:29], v[142:143] op_sel_hi:[1,0]
	v_pk_mul_f32 v[30:31], v[30:31], v[142:143] op_sel_hi:[1,0]
	v_mul_f32_e32 v28, 0xbfb8aa3b, v28
	v_mul_f32_e32 v29, 0xbfb8aa3b, v29
	v_mul_f32_e32 v30, 0xbfb8aa3b, v30
	v_mul_f32_e32 v31, 0xbfb8aa3b, v31
	v_exp_f32_e32 v28, v28
	v_exp_f32_e32 v29, v29
	v_exp_f32_e32 v30, v30
	v_exp_f32_e32 v31, v31
	v_add_f32_e32 v28, 1.0, v28
	v_add_f32_e32 v29, 1.0, v29
	v_add_f32_e32 v30, 1.0, v30
	v_add_f32_e32 v31, 1.0, v31
	v_rcp_f32_e64 v28, v28 clamp
	v_rcp_f32_e64 v29, v29 clamp
	v_rcp_f32_e64 v30, v30 clamp
	v_rcp_f32_e64 v31, v31 clamp
	v_mul_f32_e32 v28, 0x437f0000, v28
	v_mul_f32_e32 v29, 0x437f0000, v29
	v_mul_f32_e32 v30, 0x437f0000, v30
	v_mul_f32_e32 v31, 0x437f0000, v31
	v_rndne_f32_e32 v28, v28
	v_rndne_f32_e32 v29, v29
	v_rndne_f32_e32 v30, v30
	v_rndne_f32_e32 v31, v31
	v_cvt_u32_f32_e32 v28, v28
	v_cvt_u32_f32_e32 v29, v29
	v_cvt_u32_f32_sdwa v30, v30 dst_sel:WORD_1 dst_unused:UNUSED_PAD src0_sel:DWORD
	v_cvt_u32_f32_sdwa v31, v31 dst_sel:BYTE_3 dst_unused:UNUSED_PAD src0_sel:DWORD
	v_lshl_or_b32 v184, v29, 8, v28
	v_or3_b32 v184, v184, v30, v31
	v_pk_mul_f32 v[24:25], v[24:25], v[142:143] op_sel_hi:[1,0]
	v_pk_mul_f32 v[26:27], v[26:27], v[142:143] op_sel_hi:[1,0]
	v_mul_f32_e32 v24, 0xbfb8aa3b, v24
	v_mul_f32_e32 v25, 0xbfb8aa3b, v25
	v_mul_f32_e32 v26, 0xbfb8aa3b, v26
	v_mul_f32_e32 v27, 0xbfb8aa3b, v27
	v_exp_f32_e32 v24, v24
	v_exp_f32_e32 v25, v25
	v_exp_f32_e32 v26, v26
	v_exp_f32_e32 v27, v27
	v_add_f32_e32 v24, 1.0, v24
	v_add_f32_e32 v25, 1.0, v25
	v_add_f32_e32 v26, 1.0, v26
	v_add_f32_e32 v27, 1.0, v27
	v_rcp_f32_e64 v24, v24 clamp
	v_rcp_f32_e64 v25, v25 clamp
	v_rcp_f32_e64 v26, v26 clamp
	v_rcp_f32_e64 v27, v27 clamp
	v_mul_f32_e32 v24, 0x437f0000, v24
	v_mul_f32_e32 v25, 0x437f0000, v25
	v_mul_f32_e32 v26, 0x437f0000, v26
	v_mul_f32_e32 v27, 0x437f0000, v27
	v_rndne_f32_e32 v24, v24
	v_rndne_f32_e32 v25, v25
	v_rndne_f32_e32 v26, v26
	v_rndne_f32_e32 v27, v27
	v_cvt_u32_f32_e32 v24, v24
	v_cvt_u32_f32_e32 v25, v25
	v_cvt_u32_f32_sdwa v26, v26 dst_sel:WORD_1 dst_unused:UNUSED_PAD src0_sel:DWORD
	v_cvt_u32_f32_sdwa v27, v27 dst_sel:BYTE_3 dst_unused:UNUSED_PAD src0_sel:DWORD
	v_lshl_or_b32 v185, v25, 8, v24
	v_or3_b32 v185, v185, v26, v27
	v_pk_mul_f32 v[20:21], v[20:21], v[142:143] op_sel_hi:[1,0]
	v_pk_mul_f32 v[22:23], v[22:23], v[142:143] op_sel_hi:[1,0]
	v_mul_f32_e32 v20, 0xbfb8aa3b, v20
	v_mul_f32_e32 v21, 0xbfb8aa3b, v21
	v_mul_f32_e32 v22, 0xbfb8aa3b, v22
	v_mul_f32_e32 v23, 0xbfb8aa3b, v23
	v_exp_f32_e32 v20, v20
	v_exp_f32_e32 v21, v21
	v_exp_f32_e32 v22, v22
	v_exp_f32_e32 v23, v23
	v_add_f32_e32 v20, 1.0, v20
	v_add_f32_e32 v21, 1.0, v21
	v_add_f32_e32 v22, 1.0, v22
	v_add_f32_e32 v23, 1.0, v23
	v_rcp_f32_e64 v20, v20 clamp
	v_rcp_f32_e64 v21, v21 clamp
	v_rcp_f32_e64 v22, v22 clamp
	v_rcp_f32_e64 v23, v23 clamp
	v_mul_f32_e32 v20, 0x437f0000, v20
	v_mul_f32_e32 v21, 0x437f0000, v21
	v_mul_f32_e32 v22, 0x437f0000, v22
	v_mul_f32_e32 v23, 0x437f0000, v23
	v_rndne_f32_e32 v20, v20
	v_rndne_f32_e32 v21, v21
	v_rndne_f32_e32 v22, v22
	v_rndne_f32_e32 v23, v23
	v_cvt_u32_f32_e32 v20, v20
	v_cvt_u32_f32_e32 v21, v21
	v_cvt_u32_f32_sdwa v22, v22 dst_sel:WORD_1 dst_unused:UNUSED_PAD src0_sel:DWORD
	v_cvt_u32_f32_sdwa v23, v23 dst_sel:BYTE_3 dst_unused:UNUSED_PAD src0_sel:DWORD
	v_lshl_or_b32 v186, v21, 8, v20
	v_or3_b32 v186, v186, v22, v23
	v_pk_mul_f32 v[16:17], v[16:17], v[142:143] op_sel_hi:[1,0]
	v_pk_mul_f32 v[18:19], v[18:19], v[142:143] op_sel_hi:[1,0]
	v_mul_f32_e32 v16, 0xbfb8aa3b, v16
	v_mul_f32_e32 v17, 0xbfb8aa3b, v17
; __device__ __forceinline__ float sigm(float x) {
;   return __builtin_amdgcn_rcpf(1.f + __builtin_amdgcn_exp2f(-1.44269504f * x));
; }
; __device__ __forceinline__ unsigned pk4_u8(float a, float b, float c, float d) {
;   const unsigned qa = (unsigned)__builtin_rintf(fminf(fmaxf(a, 0.f), 1.f) * 255.f);
;   const unsigned qb = (unsigned)__builtin_rintf(fminf(fmaxf(b, 0.f), 1.f) * 255.f);
;   const unsigned qc = (unsigned)__builtin_rintf(fminf(fmaxf(c, 0.f), 1.f) * 255.f);
;   const unsigned qd = (unsigned)__builtin_rintf(fminf(fmaxf(d, 0.f), 1.f) * 255.f);
;   return qa | (qb << 8) | (qc << 16) | (qd << 24);
; __device__ void phase1(const Params& p) {
;     ...
;             float v[4];
;             #pragma unroll
;             for (int j = 0; j < 4; ++j) {
;               v[j] = acc[ai][bj][m][n][j] * r;
;               if (act == 2) v[j] = sigm(v[j]);
;             }
;             if (act == 2) {
;               *reinterpret_cast<unsigned*>(reinterpret_cast<unsigned char*>(dst) + (size_t)t * 2048 + (EPI_F(ai, m) - cofs)) =
;                   pk4_u8(v[0], v[1], v[2], v[3]);
	v_mul_f32_e32 v18, 0xbfb8aa3b, v18
	v_mul_f32_e32 v19, 0xbfb8aa3b, v19
	v_exp_f32_e32 v16, v16
	v_exp_f32_e32 v17, v17
	v_exp_f32_e32 v18, v18
	v_exp_f32_e32 v19, v19
	v_add_f32_e32 v16, 1.0, v16
	v_add_f32_e32 v17, 1.0, v17
	v_add_f32_e32 v18, 1.0, v18
	v_add_f32_e32 v19, 1.0, v19
	v_rcp_f32_e64 v16, v16 clamp
	v_rcp_f32_e64 v17, v17 clamp
	v_rcp_f32_e64 v18, v18 clamp
	v_rcp_f32_e64 v19, v19 clamp
	v_mul_f32_e32 v16, 0x437f0000, v16
	v_mul_f32_e32 v17, 0x437f0000, v17
	v_mul_f32_e32 v18, 0x437f0000, v18
	v_mul_f32_e32 v19, 0x437f0000, v19
	v_rndne_f32_e32 v16, v16
	v_rndne_f32_e32 v17, v17
	v_rndne_f32_e32 v18, v18
	v_rndne_f32_e32 v19, v19
	v_cvt_u32_f32_e32 v16, v16
	v_cvt_u32_f32_e32 v17, v17
	v_cvt_u32_f32_sdwa v18, v18 dst_sel:WORD_1 dst_unused:UNUSED_PAD src0_sel:DWORD
	v_cvt_u32_f32_sdwa v19, v19 dst_sel:BYTE_3 dst_unused:UNUSED_PAD src0_sel:DWORD
	v_lshl_or_b32 v187, v17, 8, v16
	v_or3_b32 v187, v187, v18, v19
	s_nop 1
	v_permlane16_swap_b32 v184, v185
	v_permlane16_swap_b32 v186, v187
	s_nop 1
	v_permlane32_swap_b32 v184, v186
	v_permlane32_swap_b32 v185, v187
	global_store_dwordx4 v151, v[184:187], s[66:67]
	v_pk_mul_f32 v[12:13], v[12:13], v[142:143] op_sel_hi:[1,0]
	v_pk_mul_f32 v[14:15], v[14:15], v[142:143] op_sel_hi:[1,0]
	v_mul_f32_e32 v12, 0xbfb8aa3b, v12
	v_mul_f32_e32 v13, 0xbfb8aa3b, v13
	v_mul_f32_e32 v14, 0xbfb8aa3b, v14
	v_mul_f32_e32 v15, 0xbfb8aa3b, v15
	v_exp_f32_e32 v12, v12
	v_exp_f32_e32 v13, v13
	v_exp_f32_e32 v14, v14
	v_exp_f32_e32 v15, v15
	v_add_f32_e32 v12, 1.0, v12
	v_add_f32_e32 v13, 1.0, v13
	v_add_f32_e32 v14, 1.0, v14
	v_add_f32_e32 v15, 1.0, v15
	v_rcp_f32_e64 v12, v12 clamp
	v_rcp_f32_e64 v13, v13 clamp
	v_rcp_f32_e64 v14, v14 clamp
	v_rcp_f32_e64 v15, v15 clamp
	v_mul_f32_e32 v12, 0x437f0000, v12
	v_mul_f32_e32 v13, 0x437f0000, v13
	v_mul_f32_e32 v14, 0x437f0000, v14
	v_mul_f32_e32 v15, 0x437f0000, v15
	v_rndne_f32_e32 v12, v12
	v_rndne_f32_e32 v13, v13
	v_rndne_f32_e32 v14, v14
	v_rndne_f32_e32 v15, v15
	v_cvt_u32_f32_e32 v12, v12
	v_cvt_u32_f32_e32 v13, v13
	v_cvt_u32_f32_sdwa v14, v14 dst_sel:WORD_1 dst_unused:UNUSED_PAD src0_sel:DWORD
	v_cvt_u32_f32_sdwa v15, v15 dst_sel:BYTE_3 dst_unused:UNUSED_PAD src0_sel:DWORD
	v_lshl_or_b32 v188, v13, 8, v12
	v_or3_b32 v188, v188, v14, v15
	v_pk_mul_f32 v[8:9], v[8:9], v[142:143] op_sel_hi:[1,0]
	v_pk_mul_f32 v[10:11], v[10:11], v[142:143] op_sel_hi:[1,0]
	v_mul_f32_e32 v8, 0xbfb8aa3b, v8
	v_mul_f32_e32 v9, 0xbfb8aa3b, v9
	v_mul_f32_e32 v10, 0xbfb8aa3b, v10
	v_mul_f32_e32 v11, 0xbfb8aa3b, v11
	v_exp_f32_e32 v8, v8
	v_exp_f32_e32 v9, v9
	v_exp_f32_e32 v10, v10
	v_exp_f32_e32 v11, v11
	v_add_f32_e32 v8, 1.0, v8
	v_add_f32_e32 v9, 1.0, v9
	v_add_f32_e32 v10, 1.0, v10
	v_add_f32_e32 v11, 1.0, v11
	v_rcp_f32_e64 v8, v8 clamp
	v_rcp_f32_e64 v9, v9 clamp
	v_rcp_f32_e64 v10, v10 clamp
	v_rcp_f32_e64 v11, v11 clamp
	v_mul_f32_e32 v8, 0x437f0000, v8
	v_mul_f32_e32 v9, 0x437f0000, v9
	v_mul_f32_e32 v10, 0x437f0000, v10
	v_mul_f32_e32 v11, 0x437f0000, v11
	v_rndne_f32_e32 v8, v8
	v_rndne_f32_e32 v9, v9
	v_rndne_f32_e32 v10, v10
	v_rndne_f32_e32 v11, v11
	v_cvt_u32_f32_e32 v8, v8
	v_cvt_u32_f32_e32 v9, v9
	v_cvt_u32_f32_sdwa v10, v10 dst_sel:WORD_1 dst_unused:UNUSED_PAD src0_sel:DWORD
	v_cvt_u32_f32_sdwa v11, v11 dst_sel:BYTE_3 dst_unused:UNUSED_PAD src0_sel:DWORD
	v_lshl_or_b32 v189, v9, 8, v8
	v_or3_b32 v189, v189, v10, v11
	v_pk_mul_f32 v[4:5], v[4:5], v[142:143] op_sel_hi:[1,0]
	v_pk_mul_f32 v[6:7], v[6:7], v[142:143] op_sel_hi:[1,0]
	v_mul_f32_e32 v4, 0xbfb8aa3b, v4
	v_mul_f32_e32 v5, 0xbfb8aa3b, v5
	v_mul_f32_e32 v6, 0xbfb8aa3b, v6
	v_mul_f32_e32 v7, 0xbfb8aa3b, v7
	v_exp_f32_e32 v4, v4
	v_exp_f32_e32 v5, v5
	v_exp_f32_e32 v6, v6
	v_exp_f32_e32 v7, v7
	v_add_f32_e32 v4, 1.0, v4
	v_add_f32_e32 v5, 1.0, v5
	v_add_f32_e32 v6, 1.0, v6
	v_add_f32_e32 v7, 1.0, v7
	v_rcp_f32_e64 v4, v4 clamp
	v_rcp_f32_e64 v5, v5 clamp
	v_rcp_f32_e64 v6, v6 clamp
	v_rcp_f32_e64 v7, v7 clamp
	v_mul_f32_e32 v4, 0x437f0000, v4
	v_mul_f32_e32 v5, 0x437f0000, v5
	v_mul_f32_e32 v6, 0x437f0000, v6
	v_mul_f32_e32 v7, 0x437f0000, v7
	v_rndne_f32_e32 v4, v4
	v_rndne_f32_e32 v5, v5
	v_rndne_f32_e32 v6, v6
	v_rndne_f32_e32 v7, v7
	v_cvt_u32_f32_e32 v4, v4
	v_cvt_u32_f32_e32 v5, v5
	v_cvt_u32_f32_sdwa v6, v6 dst_sel:WORD_1 dst_unused:UNUSED_PAD src0_sel:DWORD
	v_cvt_u32_f32_sdwa v7, v7 dst_sel:BYTE_3 dst_unused:UNUSED_PAD src0_sel:DWORD
	v_lshl_or_b32 v190, v5, 8, v4
	v_or3_b32 v190, v190, v6, v7
	v_pk_mul_f32 v[0:1], v[0:1], v[142:143] op_sel_hi:[1,0]
	v_pk_mul_f32 v[2:3], v[2:3], v[142:143] op_sel_hi:[1,0]
	v_mul_f32_e32 v0, 0xbfb8aa3b, v0
	v_mul_f32_e32 v1, 0xbfb8aa3b, v1
	v_mul_f32_e32 v2, 0xbfb8aa3b, v2
	v_mul_f32_e32 v3, 0xbfb8aa3b, v3
	v_exp_f32_e32 v0, v0
	v_exp_f32_e32 v1, v1
	v_exp_f32_e32 v2, v2
	v_exp_f32_e32 v3, v3
	v_add_f32_e32 v0, 1.0, v0
	v_add_f32_e32 v1, 1.0, v1
	v_add_f32_e32 v2, 1.0, v2
	v_add_f32_e32 v3, 1.0, v3
	v_rcp_f32_e64 v0, v0 clamp
	v_rcp_f32_e64 v1, v1 clamp
	v_rcp_f32_e64 v2, v2 clamp
	v_rcp_f32_e64 v3, v3 clamp
	v_mul_f32_e32 v0, 0x437f0000, v0
	v_mul_f32_e32 v1, 0x437f0000, v1
	v_mul_f32_e32 v2, 0x437f0000, v2
	v_mul_f32_e32 v3, 0x437f0000, v3
	v_rndne_f32_e32 v0, v0
	v_rndne_f32_e32 v1, v1
	v_rndne_f32_e32 v2, v2
	v_rndne_f32_e32 v3, v3
	v_cvt_u32_f32_e32 v0, v0
	v_cvt_u32_f32_e32 v1, v1
	v_cvt_u32_f32_sdwa v2, v2 dst_sel:WORD_1 dst_unused:UNUSED_PAD src0_sel:DWORD
	v_cvt_u32_f32_sdwa v3, v3 dst_sel:BYTE_3 dst_unused:UNUSED_PAD src0_sel:DWORD
	v_lshl_or_b32 v191, v1, 8, v0
	v_or3_b32 v191, v191, v2, v3
	s_nop 1
	v_permlane16_swap_b32 v188, v189
	v_permlane16_swap_b32 v190, v191
	s_nop 1
	v_permlane32_swap_b32 v188, v190
	v_permlane32_swap_b32 v189, v191
	global_store_dwordx4 v151, v[188:191], s[66:67] offset:128
	s_branch .LBB0_153
; __device__ void phase1(const Params& p) {
;     ...
;         const int t = EPI_T(bj, n);
;         const float r = rs[t];
;         u16* drow = dst + (size_t)t * ld - cofs;
;         #pragma unroll
;         for (int ai = 0; ai < 2; ++ai)
;           #pragma unroll
;           for (int m = 0; m < 4; ++m) {
;             float v[4];
;             #pragma unroll
;             for (int j = 0; j < 4; ++j) {
;               v[j] = acc[ai][bj][m][n][j] * r;
;               if (act == 2) v[j] = sigm(v[j]);
;             }
;             if (act == 2) {
;               *reinterpret_cast<unsigned*>(reinterpret_cast<unsigned char*>(dst) + (size_t)t * 2048 + (EPI_F(ai, m) - cofs)) =
;                   pk4_u8(v[0], v[1], v[2], v[3]);
;             } else {
;               v2u o; o.x = pk2(v[0], v[1]); o.y = pk2(v[2], v[3]);
;               *reinterpret_cast<v2u*>(drow + EPI_F(ai, m)) = o;
.Lp1e_bf16:
	s_sub_i32 s24, s6, s7
	v_and_b32_e32 v145, 1, v134
	v_lshlrev_b32_e32 v146, 2, v134
	v_mad_u32_u24 v146, v145, 12, v146
	v_add3_u32 v146, v146, v135, s24
	v_mul_lo_u32 v148, v132, s70
	v_lshl_add_u32 v148, v146, 1, v148
	s_lshl_b32 s25, s70, 4
	s_lshl_b32 s71, s70, 7
	v_add_u32_e32 v149, s25, v148
	v_add_u32_e32 v150, s71, v148
	v_add_u32_e32 v151, s25, v150
	s_waitcnt vmcnt(3)
	v_pk_mul_f32 v[124:125], v[124:125], v[136:137] op_sel_hi:[1,0]
	v_pk_mul_f32 v[126:127], v[126:127], v[136:137] op_sel_hi:[1,0]
	v_pk_mul_f32 v[120:121], v[120:121], v[136:137] op_sel_hi:[1,0]
	v_pk_mul_f32 v[122:123], v[122:123], v[136:137] op_sel_hi:[1,0]
	v_pk_mul_f32 v[116:117], v[116:117], v[136:137] op_sel_hi:[1,0]
	v_pk_mul_f32 v[118:119], v[118:119], v[136:137] op_sel_hi:[1,0]
	v_pk_mul_f32 v[112:113], v[112:113], v[136:137] op_sel_hi:[1,0]
	v_pk_mul_f32 v[114:115], v[114:115], v[136:137] op_sel_hi:[1,0]
	v_pk_mul_f32 v[108:109], v[108:109], v[136:137] op_sel_hi:[1,0]
	v_pk_mul_f32 v[110:111], v[110:111], v[136:137] op_sel_hi:[1,0]
	v_pk_mul_f32 v[104:105], v[104:105], v[136:137] op_sel_hi:[1,0]
	v_pk_mul_f32 v[106:107], v[106:107], v[136:137] op_sel_hi:[1,0]
	v_pk_mul_f32 v[100:101], v[100:101], v[136:137] op_sel_hi:[1,0]
	v_pk_mul_f32 v[102:103], v[102:103], v[136:137] op_sel_hi:[1,0]
	v_pk_mul_f32 v[96:97], v[96:97], v[136:137] op_sel_hi:[1,0]
	v_pk_mul_f32 v[98:99], v[98:99], v[136:137] op_sel_hi:[1,0]
	v_cvt_pk_bf16_f32 v124, v124, v125
	v_cvt_pk_bf16_f32 v125, v126, v127
	v_cvt_pk_bf16_f32 v126, v120, v121
	v_cvt_pk_bf16_f32 v127, v122, v123
	v_cvt_pk_bf16_f32 v116, v116, v117
	v_cvt_pk_bf16_f32 v117, v118, v119
	v_cvt_pk_bf16_f32 v118, v112, v113
	v_cvt_pk_bf16_f32 v119, v114, v115
	v_cvt_pk_bf16_f32 v108, v108, v109
	v_cvt_pk_bf16_f32 v109, v110, v111
	v_cvt_pk_bf16_f32 v110, v104, v105
	v_cvt_pk_bf16_f32 v111, v106, v107
	v_cvt_pk_bf16_f32 v100, v100, v101
	v_cvt_pk_bf16_f32 v101, v102, v103
	v_cvt_pk_bf16_f32 v102, v96, v97
	v_cvt_pk_bf16_f32 v103, v98, v99
	s_nop 1
	v_permlane16_swap_b32 v124, v126
	v_permlane16_swap_b32 v125, v127
	v_permlane16_swap_b32 v116, v118
	v_permlane16_swap_b32 v117, v119
	v_permlane16_swap_b32 v108, v110
	v_permlane16_swap_b32 v109, v111
	v_permlane16_swap_b32 v100, v102
	v_permlane16_swap_b32 v101, v103
	global_store_dwordx4 v148, v[124:127], s[66:67]
	global_store_dwordx4 v148, v[116:119], s[66:67] offset:64
	global_store_dwordx4 v148, v[108:111], s[66:67] offset:256
	global_store_dwordx4 v148, v[100:103], s[66:67] offset:320
	s_waitcnt vmcnt(6)
	v_pk_mul_f32 v[92:93], v[92:93], v[138:139] op_sel_hi:[1,0]
	v_pk_mul_f32 v[94:95], v[94:95], v[138:139] op_sel_hi:[1,0]
	v_pk_mul_f32 v[88:89], v[88:89], v[138:139] op_sel_hi:[1,0]
	v_pk_mul_f32 v[90:91], v[90:91], v[138:139] op_sel_hi:[1,0]
	v_pk_mul_f32 v[84:85], v[84:85], v[138:139] op_sel_hi:[1,0]
	v_pk_mul_f32 v[86:87], v[86:87], v[138:139] op_sel_hi:[1,0]
	v_pk_mul_f32 v[80:81], v[80:81], v[138:139] op_sel_hi:[1,0]
	v_pk_mul_f32 v[82:83], v[82:83], v[138:139] op_sel_hi:[1,0]
	v_pk_mul_f32 v[76:77], v[76:77], v[138:139] op_sel_hi:[1,0]
	v_pk_mul_f32 v[78:79], v[78:79], v[138:139] op_sel_hi:[1,0]
	v_pk_mul_f32 v[72:73], v[72:73], v[138:139] op_sel_hi:[1,0]
	v_pk_mul_f32 v[74:75], v[74:75], v[138:139] op_sel_hi:[1,0]
	v_pk_mul_f32 v[68:69], v[68:69], v[138:139] op_sel_hi:[1,0]
	v_pk_mul_f32 v[70:71], v[70:71], v[138:139] op_sel_hi:[1,0]
	v_pk_mul_f32 v[64:65], v[64:65], v[138:139] op_sel_hi:[1,0]
	v_pk_mul_f32 v[66:67], v[66:67], v[138:139] op_sel_hi:[1,0]
	v_cvt_pk_bf16_f32 v92, v92, v93
	v_cvt_pk_bf16_f32 v93, v94, v95
	v_cvt_pk_bf16_f32 v94, v88, v89
	v_cvt_pk_bf16_f32 v95, v90, v91
	v_cvt_pk_bf16_f32 v84, v84, v85
	v_cvt_pk_bf16_f32 v85, v86, v87
	v_cvt_pk_bf16_f32 v86, v80, v81
	v_cvt_pk_bf16_f32 v87, v82, v83
	v_cvt_pk_bf16_f32 v76, v76, v77
	v_cvt_pk_bf16_f32 v77, v78, v79
	v_cvt_pk_bf16_f32 v78, v72, v73
	v_cvt_pk_bf16_f32 v79, v74, v75
	v_cvt_pk_bf16_f32 v68, v68, v69
	v_cvt_pk_bf16_f32 v69, v70, v71
	v_cvt_pk_bf16_f32 v70, v64, v65
	v_cvt_pk_bf16_f32 v71, v66, v67
	s_nop 1
	v_permlane16_swap_b32 v92, v94
	v_permlane16_swap_b32 v93, v95
	v_permlane16_swap_b32 v84, v86
	v_permlane16_swap_b32 v85, v87
	v_permlane16_swap_b32 v76, v78
	v_permlane16_swap_b32 v77, v79
	v_permlane16_swap_b32 v68, v70
	v_permlane16_swap_b32 v69, v71
	global_store_dwordx4 v149, v[92:95], s[66:67]
	global_store_dwordx4 v149, v[84:87], s[66:67] offset:64
	global_store_dwordx4 v149, v[76:79], s[66:67] offset:256
	global_store_dwordx4 v149, v[68:71], s[66:67] offset:320
	s_waitcnt vmcnt(9)
; __device__ void phase1(const Params& p) {
;     ...
;         const int t = EPI_T(bj, n);
;         const float r = rs[t];
;         u16* drow = dst + (size_t)t * ld - cofs;
;         #pragma unroll
;         for (int ai = 0; ai < 2; ++ai)
;           #pragma unroll
;           for (int m = 0; m < 4; ++m) {
;             float v[4];
;             #pragma unroll
;             for (int j = 0; j < 4; ++j) {
;               v[j] = acc[ai][bj][m][n][j] * r;
;               if (act == 2) v[j] = sigm(v[j]);
;             }
;             if (act == 2) {
;               *reinterpret_cast<unsigned*>(reinterpret_cast<unsigned char*>(dst) + (size_t)t * 2048 + (EPI_F(ai, m) - cofs)) =
;                   pk4_u8(v[0], v[1], v[2], v[3]);
;             } else {
;               v2u o; o.x = pk2(v[0], v[1]); o.y = pk2(v[2], v[3]);
;               *reinterpret_cast<v2u*>(drow + EPI_F(ai, m)) = o;
	v_pk_mul_f32 v[60:61], v[60:61], v[140:141] op_sel_hi:[1,0]
	v_pk_mul_f32 v[62:63], v[62:63], v[140:141] op_sel_hi:[1,0]
	v_pk_mul_f32 v[56:57], v[56:57], v[140:141] op_sel_hi:[1,0]
	v_pk_mul_f32 v[58:59], v[58:59], v[140:141] op_sel_hi:[1,0]
	v_pk_mul_f32 v[52:53], v[52:53], v[140:141] op_sel_hi:[1,0]
	v_pk_mul_f32 v[54:55], v[54:55], v[140:141] op_sel_hi:[1,0]
	v_pk_mul_f32 v[48:49], v[48:49], v[140:141] op_sel_hi:[1,0]
	v_pk_mul_f32 v[50:51], v[50:51], v[140:141] op_sel_hi:[1,0]
	v_pk_mul_f32 v[44:45], v[44:45], v[140:141] op_sel_hi:[1,0]
	v_pk_mul_f32 v[46:47], v[46:47], v[140:141] op_sel_hi:[1,0]
	v_pk_mul_f32 v[40:41], v[40:41], v[140:141] op_sel_hi:[1,0]
	v_pk_mul_f32 v[42:43], v[42:43], v[140:141] op_sel_hi:[1,0]
	v_pk_mul_f32 v[36:37], v[36:37], v[140:141] op_sel_hi:[1,0]
	v_pk_mul_f32 v[38:39], v[38:39], v[140:141] op_sel_hi:[1,0]
	v_pk_mul_f32 v[32:33], v[32:33], v[140:141] op_sel_hi:[1,0]
	v_pk_mul_f32 v[34:35], v[34:35], v[140:141] op_sel_hi:[1,0]
	v_cvt_pk_bf16_f32 v60, v60, v61
	v_cvt_pk_bf16_f32 v61, v62, v63
	v_cvt_pk_bf16_f32 v62, v56, v57
	v_cvt_pk_bf16_f32 v63, v58, v59
	v_cvt_pk_bf16_f32 v52, v52, v53
	v_cvt_pk_bf16_f32 v53, v54, v55
	v_cvt_pk_bf16_f32 v54, v48, v49
	v_cvt_pk_bf16_f32 v55, v50, v51
	v_cvt_pk_bf16_f32 v44, v44, v45
	v_cvt_pk_bf16_f32 v45, v46, v47
	v_cvt_pk_bf16_f32 v46, v40, v41
	v_cvt_pk_bf16_f32 v47, v42, v43
	v_cvt_pk_bf16_f32 v36, v36, v37
	v_cvt_pk_bf16_f32 v37, v38, v39
	v_cvt_pk_bf16_f32 v38, v32, v33
	v_cvt_pk_bf16_f32 v39, v34, v35
	s_nop 1
	v_permlane16_swap_b32 v60, v62
	v_permlane16_swap_b32 v61, v63
	v_permlane16_swap_b32 v52, v54
	v_permlane16_swap_b32 v53, v55
	v_permlane16_swap_b32 v44, v46
	v_permlane16_swap_b32 v45, v47
	v_permlane16_swap_b32 v36, v38
	v_permlane16_swap_b32 v37, v39
	global_store_dwordx4 v150, v[60:63], s[66:67]
	global_store_dwordx4 v150, v[52:55], s[66:67] offset:64
	global_store_dwordx4 v150, v[44:47], s[66:67] offset:256
	global_store_dwordx4 v150, v[36:39], s[66:67] offset:320
	s_waitcnt vmcnt(12)
	v_pk_mul_f32 v[28:29], v[28:29], v[142:143] op_sel_hi:[1,0]
	v_pk_mul_f32 v[30:31], v[30:31], v[142:143] op_sel_hi:[1,0]
	v_pk_mul_f32 v[24:25], v[24:25], v[142:143] op_sel_hi:[1,0]
	v_pk_mul_f32 v[26:27], v[26:27], v[142:143] op_sel_hi:[1,0]
	v_pk_mul_f32 v[20:21], v[20:21], v[142:143] op_sel_hi:[1,0]
	v_pk_mul_f32 v[22:23], v[22:23], v[142:143] op_sel_hi:[1,0]
	v_pk_mul_f32 v[16:17], v[16:17], v[142:143] op_sel_hi:[1,0]
	v_pk_mul_f32 v[18:19], v[18:19], v[142:143] op_sel_hi:[1,0]
	v_pk_mul_f32 v[12:13], v[12:13], v[142:143] op_sel_hi:[1,0]
	v_pk_mul_f32 v[14:15], v[14:15], v[142:143] op_sel_hi:[1,0]
	v_pk_mul_f32 v[8:9], v[8:9], v[142:143] op_sel_hi:[1,0]
	v_pk_mul_f32 v[10:11], v[10:11], v[142:143] op_sel_hi:[1,0]
	v_pk_mul_f32 v[4:5], v[4:5], v[142:143] op_sel_hi:[1,0]
	v_pk_mul_f32 v[6:7], v[6:7], v[142:143] op_sel_hi:[1,0]
	v_pk_mul_f32 v[0:1], v[0:1], v[142:143] op_sel_hi:[1,0]
	v_pk_mul_f32 v[2:3], v[2:3], v[142:143] op_sel_hi:[1,0]
	v_cvt_pk_bf16_f32 v28, v28, v29
	v_cvt_pk_bf16_f32 v29, v30, v31
	v_cvt_pk_bf16_f32 v30, v24, v25
	v_cvt_pk_bf16_f32 v31, v26, v27
	v_cvt_pk_bf16_f32 v20, v20, v21
	v_cvt_pk_bf16_f32 v21, v22, v23
	v_cvt_pk_bf16_f32 v22, v16, v17
	v_cvt_pk_bf16_f32 v23, v18, v19
	v_cvt_pk_bf16_f32 v12, v12, v13
	v_cvt_pk_bf16_f32 v13, v14, v15
	v_cvt_pk_bf16_f32 v14, v8, v9
	v_cvt_pk_bf16_f32 v15, v10, v11
	v_cvt_pk_bf16_f32 v4, v4, v5
	v_cvt_pk_bf16_f32 v5, v6, v7
	v_cvt_pk_bf16_f32 v6, v0, v1
	v_cvt_pk_bf16_f32 v7, v2, v3
	s_nop 1
	v_permlane16_swap_b32 v28, v30
	v_permlane16_swap_b32 v29, v31
	v_permlane16_swap_b32 v20, v22
	v_permlane16_swap_b32 v21, v23
	v_permlane16_swap_b32 v12, v14
	v_permlane16_swap_b32 v13, v15
	v_permlane16_swap_b32 v4, v6
	v_permlane16_swap_b32 v5, v7
	global_store_dwordx4 v151, v[28:31], s[66:67]
	global_store_dwordx4 v151, v[20:23], s[66:67] offset:64
	global_store_dwordx4 v151, v[12:15], s[66:67] offset:256
	global_store_dwordx4 v151, v[4:7], s[66:67] offset:320
	s_branch .LBB0_153
.LBB0_172:
	s_add_i32 s6, s90, 1
	s_mul_i32 s6, s6, s33
	s_cmpk_gt_i32 s6, 0x1900
	s_cselect_b64 s[6:7], -1, 0
	s_andn2_b64 vcc, exec, s[6:7]
	s_mov_b32 s6, s35
	s_cbranch_vccz .LBB0_157
	s_branch .LBB0_158
.LBB0_305:
	s_waitcnt vmcnt(0)
	v_readlane_b32 s94, v254, 2
	v_readlane_b32 s95, v254, 3
	s_barrier
	s_and_saveexec_b64 s[0:1], s[94:95]
	s_cbranch_execz .LBB0_342
	s_mov_b64 s[6:7], exec
	v_mbcnt_lo_u32_b32 v0, s6, 0
	v_readlane_b32 s3, v254, 0
	v_mbcnt_hi_u32_b32 v0, s7, v0
	s_lshl_b32 s3, s3, 6
	s_mov_b32 s19, 0
	v_cmp_eq_u32_e32 vcc, 0, v0
	s_waitcnt vmcnt(0) expcnt(0) lgkmcnt(0)
	s_and_saveexec_b64 s[16:17], vcc
	s_cbranch_execz .LBB0_308
	s_add_i32 s18, s3, 0x500
	s_lshl_b64 s[18:19], s[18:19], 2
	s_add_u32 s18, s26, s18
	s_addc_u32 s19, s27, s19
	s_bcnt1_i32_b64 s6, s[6:7]
	v_mov_b32_e32 v1, 0
	v_mov_b32_e32 v2, s6
	global_atomic_add v1, v1, v2, s[18:19] sc0
